# P2 epilogue: per-row rstd kept in registers across a workgroup's tiles (reloaded only when the row tile changes)
# speedup vs baseline: 1.0149x; 1.0080x over previous
.LBB0_161:
	s_or_b64 exec, exec, s[0:1]
	s_xor_b64 s[0:1], s[60:61], -1
	v_writelane_b32 v255, s0, 11
	v_readlane_b32 s4, v251, 63
	v_readlane_b32 s5, v252, 0
	v_writelane_b32 v255, s1, 12
	v_writelane_b32 v255, s60, 13
	v_mov_b32_e32 v8, v210
	s_waitcnt lgkmcnt(0)
	v_cndmask_b32_e64 v0, 0, 1, s[4:5]
	v_writelane_b32 v255, s61, 14
	s_barrier
	s_mov_b32 s98, -1
	v_cmp_ne_u32_e64 s[0:1], 1, v0
	s_andn2_b64 vcc, exec, s[4:5]
	v_readfirstlane_b32 s3, v8
	s_cbranch_vccnz .LBB0_163
	v_readlane_b32 s4, v253, 24
	s_mov_b32 s40, s4
	v_readlane_b32 s4, v253, 7
	s_mov_b32 s96, s4

.LBB0_181:
	v_lshl_add_u32 v148, s96, 8, v178
	v_readlane_b32 s4, v250, 53
	v_ashrrev_i32_e32 v149, 31, v148
	v_readlane_b32 s5, v250, 54
	v_add_u32_e32 v156, 0x80, v148
	v_ashrrev_i32_e32 v157, 31, v156
	v_lshl_add_u64 v[144:145], v[148:149], 2, s[4:5]
	v_lshl_add_u64 v[146:147], v[156:157], 2, s[4:5]
	s_cmp_eq_u32 s96, s98
	s_cbranch_scc1 .Lp2_rstd_hit
	global_load_dword v240, v[144:145], off
	global_load_dword v241, v[144:145], off offset:64
	global_load_dword v242, v[144:145], off offset:128
	global_load_dword v243, v[144:145], off offset:192
	global_load_dword v244, v[146:147], off
	global_load_dword v245, v[146:147], off offset:64
	global_load_dword v246, v[146:147], off offset:128
	global_load_dword v247, v[146:147], off offset:192
	s_mov_b32 s98, s96
	s_waitcnt vmcnt(0)
.Lp2_rstd_hit:
	v_mov_b32_e32 v166, v240
	v_mov_b32_e32 v162, v241
	v_mov_b32_e32 v160, v242
	v_mov_b32_e32 v158, v243
	v_mov_b32_e32 v154, v244
	v_mov_b32_e32 v152, v245
	v_mov_b32_e32 v150, v246
	v_mov_b32_e32 v144, v247
	s_and_b64 vcc, exec, s[42:43]
	v_pk_mul_f32 v[172:173], v[56:57], v[166:167] op_sel_hi:[1,0]
	v_pk_mul_f32 v[170:171], v[60:61], v[166:167] op_sel_hi:[1,0]
	v_pk_mul_f32 v[176:177], v[58:59], v[166:167] op_sel_hi:[1,0]
	v_pk_mul_f32 v[174:175], v[62:63], v[166:167] op_sel_hi:[1,0]
	s_cbranch_vccz .LBB0_183
	v_mul_f32_e32 v64, 0xbfb8aa3b, v172
	v_exp_f32_e32 v64, v64
	v_mul_f32_e32 v145, 0xbfb8aa3b, v173
	v_exp_f32_e32 v145, v145
	v_mul_f32_e32 v147, 0xbfb8aa3b, v177
	v_add_f32_e32 v64, 1.0, v64
	v_rcp_f32_e32 v146, v64
	v_mul_f32_e32 v64, 0xbfb8aa3b, v176
	v_exp_f32_e32 v64, v64
	v_exp_f32_e32 v151, v147
	v_add_f32_e32 v145, 1.0, v145
	v_rcp_f32_e32 v147, v145
	v_add_f32_e32 v64, 1.0, v64
	v_mul_f32_e32 v145, 0xbfb8aa3b, v170
	v_rcp_f32_e32 v164, v64
	v_add_f32_e32 v64, 1.0, v151
	v_exp_f32_e32 v145, v145
	v_mul_f32_e32 v151, 0xbfb8aa3b, v171
	v_exp_f32_e32 v151, v151
	v_rcp_f32_e32 v165, v64
	v_add_f32_e32 v64, 1.0, v145
	v_mul_f32_e32 v145, 0xbfb8aa3b, v174
	v_rcp_f32_e32 v168, v64
	v_add_f32_e32 v64, 1.0, v151
	v_exp_f32_e32 v145, v145
	v_mul_f32_e32 v151, 0xbfb8aa3b, v175
	v_exp_f32_e32 v151, v151
	v_rcp_f32_e32 v169, v64
	v_add_f32_e32 v64, 1.0, v145
	v_rcp_f32_e32 v182, v64
	v_add_f32_e32 v64, 1.0, v151
	v_rcp_f32_e32 v183, v64
	v_pk_mul_f32 v[172:173], v[172:173], v[146:147]
	v_pk_mul_f32 v[176:177], v[176:177], v[164:165]
	v_pk_mul_f32 v[170:171], v[170:171], v[168:169]
	v_pk_mul_f32 v[174:175], v[174:175], v[182:183]
